# phase 2: x tile lines touched before the K-loop so the f32 residual read in the epilogue is not a cold HBM burst
# baseline (speedup 1.0000x reference)
.LBB0_168:
	v_readlane_b32 s0, v243, 19
	s_cmp_lg_u32 s0, 2
	s_cbranch_scc1 .Lxpf_skip
	v_readlane_b32 s0, v250, 2
	v_readlane_b32 s1, v250, 3
	s_lshl_b32 vcc_lo, s99, 20
	s_add_u32 s0, s0, vcc_lo
	s_addc_u32 s1, s1, 0
	s_lshl_b32 vcc_lo, s88, 10
	s_add_u32 s0, s0, vcc_lo
	s_addc_u32 s1, s1, 0
	v_lshrrev_b32_e32 v240, 3, v220
	v_lshlrev_b32_e32 v240, 12, v240
	v_and_b32_e32 v241, 7, v220
	v_lshl_or_b32 v240, v241, 7, v240
	global_load_dword v244, v240, s[0:1]
	s_add_u32 s0, s0, 0x40000
	s_addc_u32 s1, s1, 0
	global_load_dword v245, v240, s[0:1]
	s_add_u32 s0, s0, 0x40000
	s_addc_u32 s1, s1, 0
	global_load_dword v246, v240, s[0:1]
	s_add_u32 s0, s0, 0x40000
	s_addc_u32 s1, s1, 0
	global_load_dword v247, v240, s[0:1]
